# k16 + non-temporal (nt) hint on conv2d single-use v loads and in-place output stores
# baseline (speedup 1.0000x reference)
; __device__ __forceinline__ void conv2d_phase(const Frame& F, int l, bool with_ctx, bool dry) {
;     ...
;         const bool isctx = it >= NLAT;
;         const int q = isctx ? it - NLAT : it, cc = q % 11, seg = q / 11;
;         int tok0, c0, wlim; bool up_ok, dn_ok;
;         if (!isctx) { const int b = seg >> 10, r = (seg >> 3) & 127; c0 = (seg & 7) * 8; tok0 = b * SEQ + r * GRIDW + c0; wlim = GRIDW; up_ok = r > 0; dn_ok = r < SEQ / GRIDW - 1; }
;         else { const int b = seg >> 5; c0 = (seg & 31) * 8; tok0 = ML + b * CTXL + c0; wlim = CTXL; up_ok = false; dn_ok = false; }
;         const int ch = cc * 256 + lane * 4;
;         const float* wq = W9 + ch;
;         f32x4 w[9];
; #pragma unroll
;         for (int k = 0; k < 9; ++k) w[k] = *(const f32x4*)(wq + (size_t)k * FFN);
;         const f32x4 bias4 = *(const f32x4*)(Bc + ch);
;         const bf16_t* ubase = UV + (size_t)tok0 * NUP + ch;
;         u32x2 u[3][10];
; #pragma unroll
;         for (int dy = 0; dy < 3; ++dy) {
;             const bool rok = dy == 1 ? true : (dy == 0 ? up_ok : dn_ok);
; #pragma unroll
;             for (int j = 0; j < 10; ++j) {
;                 const int col = c0 - 1 + j; const bool ok = rok && col >= 0 && col < wlim;
;                 const unsigned msk = (unsigned)-(int)ok;
;                 const long off = (long)(((dy - 1) * GRIDW + (j - 1)) & (int)msk) * NUP;
;                 const u32x2 t = *(const u32x2*)(ubase + off);
;                 u[dy][j] = (u32x2){t.x & msk, t.y & msk};
;             }
;         }
.LBB0_2037:
	s_add_i32 s4, s6, -1
	s_or_b32 s5, s6, 1
	s_or_b32 s8, s6, 2
	s_or_b32 s9, s6, 3
	s_or_b32 s10, s6, 4
	s_or_b32 s11, s6, 5
	s_or_b32 s17, s6, 6
	s_or_b32 s28, s6, 7
	s_add_i32 s16, s6, 8
	s_cmp_lt_u32 s4, s7
	s_cselect_b64 s[0:1], -1, 0
	s_and_b64 s[0:1], s[0:1], exec
	s_cselect_b32 s75, -1, 0
	s_cmp_lt_u32 s16, s7
	s_cselect_b64 s[38:39], -1, 0
	s_and_b64 s[0:1], s[38:39], exec
	s_cselect_b32 s16, 0x16000, 0
	s_cmp_lt_u32 s28, s7
	s_cselect_b64 s[40:41], -1, 0
	s_and_b64 s[0:1], s[40:41], exec
	s_cselect_b32 s92, 0x13400, 0
	s_cmp_lt_u32 s17, s7
	s_cselect_b64 s[42:43], -1, 0
	s_and_b64 s[0:1], s[42:43], exec
	s_cselect_b32 s68, 0x10800, 0
	s_cmp_lt_u32 s11, s7
	s_cselect_b64 s[44:45], -1, 0
	s_and_b64 s[0:1], s[44:45], exec
	s_cselect_b32 s66, 0xdc00, 0
	s_cmp_lt_u32 s10, s7
	s_cselect_b64 s[76:77], -1, 0
	s_and_b64 s[0:1], s[76:77], exec
	s_cselect_b32 s10, 0xb000, 0
	s_cmp_lt_u32 s9, s7
	s_cselect_b64 s[82:83], -1, 0
	s_and_b64 s[0:1], s[82:83], exec
	s_cselect_b32 s62, 0x8400, 0
	s_cmp_lt_u32 s8, s7
	s_cselect_b64 s[64:65], -1, 0
	s_and_b64 s[0:1], s[64:65], exec
	s_cselect_b32 s88, 0x5800, 0
	s_cmp_lt_u32 s5, s7
	s_cselect_b64 vcc, -1, 0
	s_and_b64 s[0:1], vcc, exec
	s_cselect_b32 s28, 0x2c00, 0
	s_cmp_lt_u32 s4, s7
	s_cselect_b64 s[0:1], -1, 0
	s_mul_i32 s3, s3, 11
	s_and_b64 s[4:5], s[0:1], exec
	s_cselect_b32 s74, 0xffffd400, 0
	s_sub_i32 s2, s2, s3
	v_lshl_add_u32 v42, s2, 8, v0
	v_ashrrev_i32_e32 v43, 31, v42
	v_readlane_b32 s2, v255, 21
	v_lshlrev_b64 v[38:39], 2, v[42:43]
	v_readlane_b32 s3, v255, 22
	v_readlane_b32 s4, v254, 19
	v_readlane_b32 s5, v254, 20
	s_waitcnt lgkmcnt(0)
	v_lshl_add_u64 v[2:3], s[2:3], 0, v[38:39]
	s_movk_i32 s2, 0x2000
	v_add_co_u32_e64 v4, s[2:3], s2, v2
	s_mov_b32 s11, s29
	s_nop 0
	v_addc_co_u32_e64 v5, s[2:3], 0, v3, s[2:3]
	s_movk_i32 s2, 0x5000
	s_nop 0
	v_add_co_u32_e64 v6, s[2:3], s2, v2
	s_mov_b32 s89, s29
	s_nop 0
	v_addc_co_u32_e64 v7, s[2:3], 0, v3, s[2:3]
	s_mov_b32 s2, 0x8000
	s_nop 0
	v_add_co_u32_e64 v8, s[2:3], s2, v2
	s_mov_b32 s63, s29
	s_nop 0
	v_addc_co_u32_e64 v9, s[2:3], 0, v3, s[2:3]
	s_mov_b32 s2, 0xb000
	s_nop 0
	v_add_co_u32_e64 v10, s[2:3], s2, v2
	s_mov_b32 s67, s29
	s_nop 0
	v_addc_co_u32_e64 v11, s[2:3], 0, v3, s[2:3]
	s_mov_b32 s2, 0xd000
	s_nop 0
	v_add_co_u32_e64 v12, s[2:3], s2, v2
	s_mov_b32 s69, s29
	s_nop 0
	v_addc_co_u32_e64 v13, s[2:3], 0, v3, s[2:3]
	s_mov_b32 s2, 0x10000
	s_nop 0
	v_add_co_u32_e64 v14, s[2:3], s2, v2
	s_mov_b32 s93, s29
	s_nop 0
	v_addc_co_u32_e64 v15, s[2:3], 0, v3, s[2:3]
	s_mov_b32 s2, 0x13000
	s_nop 0
	v_add_co_u32_e64 v40, s[2:3], s2, v2
	s_mov_b32 s17, s29
	s_nop 0
	v_addc_co_u32_e64 v41, s[2:3], 0, v3, s[2:3]
	s_mov_b32 s2, 0x16000
	s_nop 0
	v_add_co_u32_e64 v44, s[2:3], s2, v2
	s_mov_b32 s36, 0x3f07dc22
	s_nop 0
	v_addc_co_u32_e64 v45, s[2:3], 0, v3, s[2:3]
	s_mul_i32 s2, s27, 0x2c00
	s_mul_hi_i32 s3, s27, 0x2c00
	s_add_u32 s2, s4, s2
	s_addc_u32 s3, s5, s3
	s_and_b64 s[4:5], s[70:71], s[0:1]
	v_lshl_add_u64 v[68:69], v[42:43], 1, s[2:3]
	s_and_b64 s[2:3], s[4:5], exec
	s_cselect_b32 s3, -1, 0
	s_cselect_b32 s2, 0xfff4d400, 0
	v_lshl_add_u64 v[16:17], v[68:69], 0, s[2:3]
	global_load_dwordx2 v[16:17], v[16:17], off
	s_cmp_lt_u32 s6, s7
	s_cselect_b64 s[2:3], -1, 0
	s_and_b64 s[6:7], s[70:71], s[2:3]
	s_and_b64 s[8:9], s[6:7], exec
	s_cselect_b32 s9, -1, 0
	s_cselect_b32 s8, 0xfff50000, 0
	v_lshl_add_u64 v[18:19], v[68:69], 0, s[8:9]
	s_and_b64 s[8:9], s[70:71], vcc
	s_and_b64 s[72:73], s[8:9], exec
	s_cselect_b32 s73, -1, 0
	s_cselect_b32 s72, 0xfff52c00, 0
	v_lshl_add_u64 v[20:21], v[68:69], 0, s[72:73]
	s_and_b64 s[46:47], s[70:71], s[64:65]
	s_and_b64 s[72:73], s[46:47], exec
	s_cselect_b32 s73, -1, 0
	s_cselect_b32 s72, 0xfff55800, 0
	v_lshl_add_u64 v[46:47], v[68:69], 0, s[72:73]
	v_lshl_add_u64 v[70:71], v[68:69], 0, s[10:11]
	v_lshl_add_u64 v[62:63], v[68:69], 0, s[88:89]
	v_lshl_add_u64 v[64:65], v[68:69], 0, s[62:63]
	s_mov_b64 s[50:51], s[46:47]
	s_mov_b32 s46, 0xbf38aa3b
	s_mov_b64 s[88:89], s[44:45]
	global_load_dwordx2 v[150:151], v[18:19], off
	global_load_dwordx2 v[152:153], v[20:21], off
	v_lshl_add_u64 v[154:155], v[68:69], 0, s[74:75]
	v_lshl_add_u64 v[162:163], v[68:69], 0, s[28:29]
	global_load_dwordx2 v[156:157], v[154:155], off
	global_load_dwordx2 v[158:159], v[68:69], off
	global_load_dwordx2 v[160:161], v[162:163], off
	s_waitcnt vmcnt(5)
	v_cndmask_b32_e64 v109, 0, v16, s[4:5]
	v_cndmask_b32_e64 v108, 0, v17, s[4:5]
	v_lshlrev_b32_e32 v110, 16, v109
	v_and_b32_e32 v111, 0xffff0000, v109
	s_waitcnt vmcnt(4)
	v_cndmask_b32_e64 v107, 0, v150, s[6:7]
	v_cndmask_b32_e64 v106, 0, v151, s[6:7]
	v_lshlrev_b32_e32 v116, 16, v107
	v_and_b32_e32 v117, 0xffff0000, v107
	v_lshlrev_b32_e32 v118, 16, v106
	v_and_b32_e32 v119, 0xffff0000, v106
	s_waitcnt vmcnt(3)
	v_cndmask_b32_e64 v105, 0, v152, s[8:9]
	v_cndmask_b32_e64 v104, 0, v153, s[8:9]
	s_and_b64 s[8:9], s[70:71], s[82:83]
	s_and_b64 s[4:5], s[8:9], exec
	s_cselect_b32 s5, -1, 0
	s_cselect_b32 s4, 0xfff58400, 0
	s_and_b64 s[6:7], s[70:71], s[76:77]
	v_lshl_add_u64 v[48:49], v[68:69], 0, s[4:5]
	s_and_b64 s[4:5], s[6:7], exec
	s_cselect_b32 s5, -1, 0
	s_cselect_b32 s4, 0xfff5b000, 0
	v_lshl_add_u64 v[50:51], v[68:69], 0, s[4:5]
	s_and_b64 s[4:5], s[70:71], s[44:45]
	v_writelane_b32 v255, s4, 27
	v_lshlrev_b32_e32 v112, 16, v104
	v_and_b32_e32 v113, 0xffff0000, v104
	v_writelane_b32 v255, s5, 28
	s_and_b64 s[4:5], s[4:5], exec
	s_cselect_b32 s5, -1, 0
	s_cselect_b32 s4, 0xfff5dc00, 0
	v_lshl_add_u64 v[52:53], v[68:69], 0, s[4:5]
	s_and_b64 s[4:5], s[70:71], s[42:43]
	v_writelane_b32 v255, s4, 25
	s_mov_b64 s[74:75], s[42:43]
	s_waitcnt vmcnt(2)
; __device__ __forceinline__ void conv2d_phase(const Frame& F, int l, bool with_ctx, bool dry) {
;     ...
;         for (int k = 0; k < 9; ++k) w[k] = *(const f32x4*)(wq + (size_t)k * FFN);
;         const f32x4 bias4 = *(const f32x4*)(Bc + ch);
;         const bf16_t* ubase = UV + (size_t)tok0 * NUP + ch;
;         u32x2 u[3][10];
; #pragma unroll
;         for (int dy = 0; dy < 3; ++dy) {
;             const bool rok = dy == 1 ? true : (dy == 0 ? up_ok : dn_ok);
; #pragma unroll
;             for (int j = 0; j < 10; ++j) {
;                 const int col = c0 - 1 + j; const bool ok = rok && col >= 0 && col < wlim;
;                 const unsigned msk = (unsigned)-(int)ok;
;                 const long off = (long)(((dy - 1) * GRIDW + (j - 1)) & (int)msk) * NUP;
;                 const u32x2 t = *(const u32x2*)(ubase + off);
;                 u[dy][j] = (u32x2){t.x & msk, t.y & msk};
;             }
;         }
;         u32x2 vv[8];
; #pragma unroll
;         for (int t = 0; t < 8; ++t) vv[t] = *(const u32x2*)(ubase + (size_t)t * NUP + FFN);
	v_cndmask_b32_e64 v123, 0, v156, s[0:1]
	v_writelane_b32 v255, s5, 26
	s_and_b64 s[4:5], s[4:5], exec
	s_cselect_b32 s5, -1, 0
	s_cselect_b32 s4, 0xfff60800, 0
	v_lshl_add_u64 v[54:55], v[68:69], 0, s[4:5]
	s_and_b64 s[4:5], s[70:71], s[40:41]
	v_writelane_b32 v255, s4, 23
	v_cndmask_b32_e64 v120, 0, v157, s[0:1]
	s_waitcnt vmcnt(1)
	v_cndmask_b32_e64 v121, 0, v158, s[2:3]
	v_writelane_b32 v255, s5, 24
	s_and_b64 s[4:5], s[4:5], exec
	s_cselect_b32 s5, -1, 0
	s_cselect_b32 s4, 0xfff63400, 0
	s_and_b64 s[72:73], s[70:71], s[38:39]
	v_lshl_add_u64 v[56:57], v[68:69], 0, s[4:5]
	s_and_b64 s[4:5], s[72:73], exec
	s_cselect_b32 s5, -1, 0
	s_cselect_b32 s4, 0xfff66000, 0
	s_and_b64 s[0:1], s[30:31], s[0:1]
	v_lshl_add_u64 v[58:59], v[68:69], 0, s[4:5]
	s_and_b64 s[4:5], s[0:1], exec
	v_cndmask_b32_e64 v122, 0, v159, s[2:3]
	s_cselect_b32 s28, 0xad400, 0
	s_and_b64 s[2:3], s[30:31], s[2:3]
	s_and_b64 s[4:5], s[2:3], exec
	v_lshl_add_u64 v[16:17], v[68:69], 0, s[28:29]
	s_cselect_b32 s28, 0xb0000, 0
	global_load_dwordx2 v[72:73], v[16:17], off
	v_lshl_add_u64 v[16:17], v[68:69], 0, s[28:29]
	global_load_dwordx2 v[74:75], v[16:17], off
	s_waitcnt vmcnt(2)
	v_cndmask_b32_e32 v115, 0, v160, vcc
	v_cndmask_b32_e32 v114, 0, v161, vcc
	s_and_b64 vcc, s[30:31], vcc
	s_and_b64 s[4:5], vcc, exec
	s_cselect_b32 s28, 0xb2c00, 0
	v_lshl_add_u64 v[16:17], v[68:69], 0, s[28:29]
	global_load_dwordx2 v[76:77], v[16:17], off
	global_load_dwordx4 v[34:37], v[2:3], off
	global_load_dwordx4 v[18:21], v[4:5], off offset:3072
	global_load_dwordx4 v[22:25], v[6:7], off offset:2048
	global_load_dwordx4 v[26:29], v[8:9], off offset:1024
	global_load_dwordx4 v[30:33], v[10:11], off
	s_nop 0
	global_load_dwordx4 v[10:13], v[12:13], off offset:3072
	s_nop 0
	global_load_dwordx4 v[14:17], v[14:15], off offset:2048
	s_nop 0
	global_load_dwordx4 v[2:5], v[40:41], off offset:1024
	global_load_dwordx4 v[6:9], v[44:45], off
	v_readlane_b32 s4, v255, 55
	v_readlane_b32 s5, v255, 56
	v_lshlrev_b32_e32 v138, 16, v123
	v_and_b32_e32 v139, 0xffff0000, v123
	v_lshl_add_u64 v[38:39], s[4:5], 0, v[38:39]
	s_and_b64 s[4:5], s[30:31], s[64:65]
	global_load_dwordx4 v[38:41], v[38:39], off
	s_nop 0
	global_load_dwordx2 v[92:93], v[46:47], off
	global_load_dwordx2 v[80:81], v[48:49], off
	global_load_dwordx2 v[66:67], v[50:51], off
	global_load_dwordx2 v[60:61], v[52:53], off
	s_nop 0
	global_load_dwordx2 v[54:55], v[54:55], off
	s_nop 0
	global_load_dwordx2 v[48:49], v[56:57], off
	global_load_dwordx2 v[44:45], v[58:59], off
	global_load_dwordx2 v[94:95], v[62:63], off
	global_load_dwordx2 v[82:83], v[64:65], off
	s_nop 0
	global_load_dwordx2 v[70:71], v[70:71], off
	v_lshl_add_u64 v[46:47], v[68:69], 0, s[66:67]
	global_load_dwordx2 v[64:65], v[46:47], off
	v_lshlrev_b32_e32 v140, 16, v120
	v_and_b32_e32 v141, 0xffff0000, v120
	v_lshlrev_b32_e32 v120, 16, v121
	v_and_b32_e32 v121, 0xffff0000, v121
	v_lshlrev_b32_e32 v104, 16, v115
	v_lshlrev_b32_e32 v124, 16, v122
	v_and_b32_e32 v125, 0xffff0000, v122
	v_lshlrev_b32_e32 v106, 16, v114
	v_and_b32_e32 v107, 0xffff0000, v114
	s_mov_b64 s[66:67], s[38:39]
	s_mov_b64 s[70:71], s[40:41]
	s_waitcnt vmcnt(23)
	v_cndmask_b32_e64 v133, 0, v72, s[0:1]
	v_cndmask_b32_e64 v132, 0, v73, s[0:1]
	s_and_b64 s[0:1], s[4:5], exec
	s_waitcnt vmcnt(22)
	v_cndmask_b32_e64 v126, 0, v74, s[2:3]
	v_cndmask_b32_e64 v127, 0, v75, s[2:3]
	s_cselect_b32 s28, 0xb5800, 0
	s_and_b64 s[2:3], s[30:31], s[82:83]
	s_and_b64 s[0:1], s[2:3], exec
	v_lshl_add_u64 v[50:51], v[68:69], 0, s[28:29]
	s_cselect_b32 s28, 0xb8400, 0
	s_and_b64 s[0:1], s[30:31], s[76:77]
	s_and_b64 s[10:11], s[0:1], exec
	global_load_dwordx2 v[100:101], v[50:51], off
	v_lshl_add_u64 v[50:51], v[68:69], 0, s[28:29]
	s_cselect_b32 s28, 0xbb000, 0
	s_and_b64 s[62:63], s[30:31], s[44:45]
	v_lshl_add_u64 v[46:47], v[68:69], 0, s[68:69]
	s_and_b64 s[10:11], s[62:63], exec
	global_load_dwordx2 v[58:59], v[46:47], off
	global_load_dwordx2 v[90:91], v[50:51], off
	v_lshl_add_u64 v[50:51], v[68:69], 0, s[28:29]
	s_cselect_b32 s28, 0xbdc00, 0
	s_and_b64 s[68:69], s[30:31], s[42:43]
	v_lshl_add_u64 v[46:47], v[68:69], 0, s[92:93]
	s_and_b64 s[10:11], s[68:69], exec
	global_load_dwordx2 v[52:53], v[46:47], off
	global_load_dwordx2 v[84:85], v[50:51], off
	v_lshl_add_u64 v[46:47], v[68:69], 0, s[16:17]
	v_lshl_add_u64 v[50:51], v[68:69], 0, s[28:29]
	s_cselect_b32 s28, 0xc0800, 0
	s_and_b64 s[16:17], s[30:31], s[40:41]
	s_and_b64 s[10:11], s[16:17], exec
	global_load_dwordx2 v[46:47], v[46:47], off
	s_waitcnt vmcnt(27)
	v_cndmask_b32_e32 v131, 0, v76, vcc
	global_load_dwordx2 v[72:73], v[50:51], off
	v_lshl_add_u64 v[50:51], v[68:69], 0, s[28:29]
	s_cselect_b32 s28, 0xc3400, 0
	s_and_b64 s[10:11], s[30:31], s[38:39]
	s_and_b64 s[30:31], s[10:11], exec
	global_load_dwordx2 v[62:63], v[50:51], off
	v_lshl_add_u64 v[50:51], v[68:69], 0, s[28:29]
	s_cselect_b32 s28, 0xc6000, 0
	global_load_dwordx2 v[56:57], v[50:51], off
	v_lshl_add_u64 v[50:51], v[68:69], 0, s[28:29]
	s_movk_i32 s28, 0x1000
	v_cndmask_b32_e32 v130, 0, v77, vcc
	v_add_co_u32_e32 v74, vcc, s28, v68
	s_movk_i32 s28, 0x4000
	s_nop 0
	v_addc_co_u32_e32 v75, vcc, 0, v69, vcc
	global_load_dwordx2 v[102:103], v[74:75], off offset:1536 nt
	v_add_co_u32_e32 v74, vcc, s28, v68
	s_movk_i32 s28, 0x6000
	s_nop 0
	v_addc_co_u32_e32 v75, vcc, 0, v69, vcc
	global_load_dwordx2 v[50:51], v[50:51], off
	s_waitcnt vmcnt(22)
; __device__ __forceinline__ unsigned pk2(float lo, float hi) { const f32x2 v = {lo, hi}; const bf16x2_t b = __builtin_convertvector(v, bf16x2_t); return __builtin_bit_cast(unsigned, b); }
; __device__ __forceinline__ void conv2d_phase(const Frame& F, int l, bool with_ctx, bool dry) {
;     ...
;         for (int t = 0; t < 8; ++t) vv[t] = *(const u32x2*)(ubase + (size_t)t * NUP + FFN);
; #pragma unroll
;         for (int t = 0; t < 8; ++t) {
;             f32x4 a = bias4;
; #pragma unroll
;             for (int dy = 0; dy < 3; ++dy)
; #pragma unroll
;                 for (int dx = 0; dx < 3; ++dx) {
;                     const u32x2 x = u[dy][t + dx]; const f32x4 ww = w[dy * 3 + dx];
;                     a.x += ww.x * bflo(x.x); a.y += ww.y * bfhi(x.x); a.z += ww.z * bflo(x.y); a.w += ww.w * bfhi(x.y);
;                 }
;             const f32x2 g0 = gelu_pk((f32x2){a.x, a.y}), g1 = gelu_pk((f32x2){a.z, a.w});
;             u32x2 o; o.x = pk2(g0.x * bflo(vv[t].x), g0.y * bfhi(vv[t].x)); o.y = pk2(g1.x * bflo(vv[t].y), g1.y * bfhi(vv[t].y));
;             bf16_t* vp = UV + (size_t)(tok0 + t) * NUP + FFN + ch;
;             if (!dry) *(u32x2*)vp = o; else asm volatile("" :: "v"(o));
	v_pk_fma_f32 v[134:135], v[34:35], v[110:111], v[38:39]
	global_load_dwordx2 v[96:97], v[74:75], off offset:512 nt
	v_add_co_u32_e32 v74, vcc, s28, v68
	s_mov_b32 s28, 0x9000
	s_nop 0
	v_addc_co_u32_e32 v75, vcc, 0, v69, vcc
	global_load_dwordx2 v[98:99], v[74:75], off offset:3584 nt
	v_add_co_u32_e32 v74, vcc, s28, v68
	s_mov_b32 s28, 0xc000
	s_nop 0
	v_addc_co_u32_e32 v75, vcc, 0, v69, vcc
	global_load_dwordx2 v[86:87], v[74:75], off offset:2560 nt
	v_add_co_u32_e32 v74, vcc, s28, v68
	s_mov_b32 s28, 0xf000
	s_nop 0
	v_addc_co_u32_e32 v75, vcc, 0, v69, vcc
	global_load_dwordx2 v[76:77], v[74:75], off offset:1536 nt
	v_add_co_u32_e32 v74, vcc, s28, v68
	s_mov_b32 s28, 0x11000
	s_nop 0
	v_addc_co_u32_e32 v75, vcc, 0, v69, vcc
	global_load_dwordx2 v[88:89], v[74:75], off offset:512 nt
	v_add_co_u32_e32 v74, vcc, s28, v68
	s_mov_b32 s28, 0x14000
	s_nop 0
	v_addc_co_u32_e32 v75, vcc, 0, v69, vcc
	global_load_dwordx2 v[78:79], v[74:75], off offset:3584 nt
	v_add_co_u32_e32 v74, vcc, s28, v68
	v_lshlrev_b32_e32 v110, 16, v108
	s_nop 0
	v_addc_co_u32_e32 v75, vcc, 0, v69, vcc
	global_load_dwordx2 v[74:75], v[74:75], off offset:2560 nt
	v_and_b32_e32 v111, 0xffff0000, v108
	v_pk_fma_f32 v[136:137], v[36:37], v[110:111], v[40:41]
	v_lshlrev_b32_e32 v110, 16, v105
	v_and_b32_e32 v111, 0xffff0000, v105
	v_lshlrev_b32_e32 v142, 16, v133
	v_and_b32_e32 v143, 0xffff0000, v133
	v_lshlrev_b32_e32 v144, 16, v132
	v_and_b32_e32 v145, 0xffff0000, v132
	v_pk_fma_f32 v[132:133], v[18:19], v[116:117], v[134:135]
	v_and_b32_e32 v105, 0xffff0000, v115
	v_pk_fma_f32 v[132:133], v[22:23], v[110:111], v[132:133]
	v_lshlrev_b32_e32 v122, 16, v126
	v_pk_fma_f32 v[132:133], v[26:27], v[138:139], v[132:133]
	v_and_b32_e32 v123, 0xffff0000, v126
	v_pk_fma_f32 v[132:133], v[30:31], v[120:121], v[132:133]
	v_lshlrev_b32_e32 v108, 16, v131
	v_pk_fma_f32 v[132:133], v[10:11], v[104:105], v[132:133]
	v_and_b32_e32 v109, 0xffff0000, v131
	v_pk_fma_f32 v[132:133], v[14:15], v[142:143], v[132:133]
	s_mov_b32 s28, 0x3e6d3388
	v_pk_fma_f32 v[132:133], v[2:3], v[122:123], v[132:133]
	v_lshlrev_b32_e32 v114, 16, v130
	v_pk_fma_f32 v[132:133], v[6:7], v[108:109], v[132:133]
	v_and_b32_e32 v115, 0xffff0000, v130
	v_and_b32_e32 v135, 0x7fffffff, v133
	v_and_b32_e32 v134, 0x7fffffff, v132
	v_pk_fma_f32 v[134:135], v[134:135], s[28:29], 1.0 op_sel_hi:[1,0,0]
	v_pk_fma_f32 v[130:131], v[20:21], v[118:119], v[136:137]
	v_rcp_f32_e32 v134, v134
	v_rcp_f32_e32 v135, v135
	v_pk_fma_f32 v[130:131], v[24:25], v[112:113], v[130:131]
	s_mov_b32 s38, 0xbf3a00e3
	v_pk_fma_f32 v[130:131], v[28:29], v[140:141], v[130:131]
	v_mov_b64_e32 v[136:137], s[38:39]
	v_pk_mul_f32 v[140:141], v[132:133], v[132:133]
	v_pk_fma_f32 v[130:131], v[32:33], v[124:125], v[130:131]
	v_pk_fma_f32 v[138:139], v[134:135], s[36:37], v[136:137] op_sel_hi:[1,0,0]
	s_mov_b32 s40, 0x3f35f0e3
	v_pk_mul_f32 v[140:141], v[140:141], s[46:47] op_sel_hi:[1,0]
	v_pk_fma_f32 v[130:131], v[12:13], v[106:107], v[130:131]
	v_pk_fma_f32 v[138:139], v[134:135], v[138:139], s[40:41] op_sel_hi:[1,1,0]
	s_mov_b32 s42, 0xbe11a98e
	v_exp_f32_e32 v140, v140
	v_exp_f32_e32 v141, v141
	v_lshlrev_b32_e32 v126, 16, v127
	v_and_b32_e32 v127, 0xffff0000, v127
	v_pk_fma_f32 v[130:131], v[16:17], v[144:145], v[130:131]
	v_pk_fma_f32 v[138:139], v[134:135], v[138:139], s[42:43] op_sel_hi:[1,1,0]
	s_mov_b32 s44, 0x3e027906
	v_pk_fma_f32 v[130:131], v[4:5], v[126:127], v[130:131]
	v_pk_fma_f32 v[138:139], v[134:135], v[138:139], s[44:45] op_sel_hi:[1,1,0]
	v_pk_fma_f32 v[130:131], v[8:9], v[114:115], v[130:131]
	v_pk_mul_f32 v[134:135], v[134:135], v[138:139]
	v_cmp_gt_f32_e32 vcc, 0, v133
	v_pk_mul_f32 v[134:135], v[140:141], v[134:135]
	v_and_b32_e32 v141, 0x7fffffff, v131
	v_and_b32_e32 v140, 0x7fffffff, v130
	v_pk_fma_f32 v[140:141], v[140:141], s[28:29], 1.0 op_sel_hi:[1,0,0]
	v_pk_mul_f32 v[138:139], v[132:133], v[134:135]
	v_rcp_f32_e32 v140, v140
	v_rcp_f32_e32 v141, v141
	v_pk_fma_f32 v[134:135], v[132:133], v[134:135], v[132:133] neg_lo:[1,0,0] neg_hi:[1,0,0]
	s_mov_b64 s[30:31], -1
	v_cndmask_b32_e32 v133, v135, v139, vcc
	v_cmp_gt_f32_e32 vcc, 0, v132
	s_waitcnt vmcnt(8)
	v_and_b32_e32 v139, 0xffff0000, v102
	v_cndmask_b32_e32 v132, v134, v138, vcc
	v_pk_fma_f32 v[134:135], v[140:141], s[36:37], v[136:137] op_sel_hi:[1,0,0]
	v_pk_mul_f32 v[136:137], v[130:131], v[130:131]
	v_pk_fma_f32 v[134:135], v[140:141], v[134:135], s[40:41] op_sel_hi:[1,1,0]
	v_pk_mul_f32 v[136:137], v[136:137], s[46:47] op_sel_hi:[1,0]
	v_pk_fma_f32 v[134:135], v[140:141], v[134:135], s[42:43] op_sel_hi:[1,1,0]
	v_exp_f32_e32 v136, v136
	v_exp_f32_e32 v137, v137
	v_pk_fma_f32 v[134:135], v[140:141], v[134:135], s[44:45] op_sel_hi:[1,1,0]
	v_cmp_gt_f32_e32 vcc, 0, v131
	v_pk_mul_f32 v[134:135], v[140:141], v[134:135]
	v_lshlrev_b32_e32 v138, 16, v102
	v_pk_mul_f32 v[134:135], v[136:137], v[134:135]
	v_pk_mul_f32 v[132:133], v[132:133], v[138:139]
	v_pk_mul_f32 v[136:137], v[130:131], v[134:135]
	v_pk_fma_f32 v[134:135], v[130:131], v[134:135], v[130:131] neg_lo:[1,0,0] neg_hi:[1,0,0]
	v_cvt_pk_bf16_f32 v102, v132, v133
	v_cndmask_b32_e32 v131, v135, v137, vcc
	v_cmp_gt_f32_e32 vcc, 0, v130
	v_lshlrev_b32_e32 v132, 16, v103
	v_and_b32_e32 v133, 0xffff0000, v103
	v_cndmask_b32_e32 v130, v134, v136, vcc
	v_pk_mul_f32 v[130:131], v[130:131], v[132:133]
	s_and_b64 vcc, exec, s[48:49]
	v_cvt_pk_bf16_f32 v103, v130, v131
	s_cbranch_vccz .LBB0_2039
	s_mov_b64 s[30:31], 0
.LBB0_2039:
	s_andn2_b64 vcc, exec, s[30:31]
	s_cbranch_vccnz .LBB0_2041
	v_add_co_u32_e32 v68, vcc, 0x1000, v68
	s_nop 1
	v_addc_co_u32_e32 v69, vcc, 0, v69, vcc
	global_store_dwordx2 v[68:69], v[102:103], off offset:1536 nt

; __device__ __forceinline__ unsigned pk2(float lo, float hi) { const f32x2 v = {lo, hi}; const bf16x2_t b = __builtin_convertvector(v, bf16x2_t); return __builtin_bit_cast(unsigned, b); }
; __device__ __forceinline__ void conv2d_phase(const Frame& F, int l, bool with_ctx, bool dry) {
;     ...
;             u32x2 o; o.x = pk2(g0.x * bflo(vv[t].x), g0.y * bfhi(vv[t].x)); o.y = pk2(g1.x * bflo(vv[t].y), g1.y * bfhi(vv[t].y));
;             bf16_t* vp = UV + (size_t)(tok0 + t) * NUP + FFN + ch;
;             if (!dry) *(u32x2*)vp = o; else asm volatile("" :: "v"(o));
.LBB0_2043:
	s_andn2_b64 vcc, exec, s[4:5]
	s_mov_b64 s[64:65], 0x80
	s_cbranch_vccnz .LBB0_2045
	s_add_i32 s4, s27, 1
	s_mul_hi_i32 s5, s4, 0x2c00
	s_mulk_i32 s4, 0x2c00
	v_readlane_b32 s30, v254, 19
	v_readlane_b32 s31, v254, 20
	s_add_u32 s4, s30, s4
	s_addc_u32 s5, s31, s5
	v_lshl_add_u64 v[102:103], v[42:43], 1, s[4:5]
	v_add_co_u32_e32 v102, vcc, 0x1000, v102
	s_nop 1
	v_addc_co_u32_e32 v103, vcc, 0, v103, vcc
	global_store_dwordx2 v[102:103], v[96:97], off offset:1536 nt

; __device__ __forceinline__ unsigned pk2(float lo, float hi) { const f32x2 v = {lo, hi}; const bf16x2_t b = __builtin_convertvector(v, bf16x2_t); return __builtin_bit_cast(unsigned, b); }
; __device__ __forceinline__ void conv2d_phase(const Frame& F, int l, bool with_ctx, bool dry) {
;     ...
;             u32x2 o; o.x = pk2(g0.x * bflo(vv[t].x), g0.y * bfhi(vv[t].x)); o.y = pk2(g1.x * bflo(vv[t].y), g1.y * bfhi(vv[t].y));
;             bf16_t* vp = UV + (size_t)(tok0 + t) * NUP + FFN + ch;
;             if (!dry) *(u32x2*)vp = o; else asm volatile("" :: "v"(o));
.LBB0_2047:
	s_andn2_b64 vcc, exec, s[2:3]
	s_cbranch_vccnz .LBB0_2049
	s_add_i32 s2, s27, 2
	s_mul_hi_i32 s3, s2, 0x2c00
	s_mulk_i32 s2, 0x2c00
	v_readlane_b32 s4, v254, 19
	v_readlane_b32 s5, v254, 20
	s_add_u32 s2, s4, s2
	s_addc_u32 s3, s5, s3
	v_lshl_add_u64 v[98:99], v[42:43], 1, s[2:3]
	v_add_co_u32_e32 v98, vcc, 0x1000, v98
	s_nop 1
	v_addc_co_u32_e32 v99, vcc, 0, v99, vcc
	global_store_dwordx2 v[98:99], v[96:97], off offset:1536 nt

; __device__ __forceinline__ unsigned pk2(float lo, float hi) { const f32x2 v = {lo, hi}; const bf16x2_t b = __builtin_convertvector(v, bf16x2_t); return __builtin_bit_cast(unsigned, b); }
; __device__ __forceinline__ void conv2d_phase(const Frame& F, int l, bool with_ctx, bool dry) {
;     ...
;             u32x2 o; o.x = pk2(g0.x * bflo(vv[t].x), g0.y * bfhi(vv[t].x)); o.y = pk2(g1.x * bflo(vv[t].y), g1.y * bfhi(vv[t].y));
;             bf16_t* vp = UV + (size_t)(tok0 + t) * NUP + FFN + ch;
;             if (!dry) *(u32x2*)vp = o; else asm volatile("" :: "v"(o));
.LBB0_2051:
	s_andn2_b64 vcc, exec, s[0:1]
	s_cbranch_vccnz .LBB0_2053
	s_add_i32 s0, s27, 3
	s_mul_hi_i32 s1, s0, 0x2c00
	s_mulk_i32 s0, 0x2c00
	v_readlane_b32 s2, v254, 19
	v_readlane_b32 s3, v254, 20
	s_add_u32 s0, s2, s0
	s_addc_u32 s1, s3, s1
	v_lshl_add_u64 v[86:87], v[42:43], 1, s[0:1]
	v_add_co_u32_e32 v86, vcc, 0x1000, v86
	s_nop 1
	v_addc_co_u32_e32 v87, vcc, 0, v87, vcc
	global_store_dwordx2 v[86:87], v[68:69], off offset:1536 nt

; __device__ __forceinline__ unsigned pk2(float lo, float hi) { const f32x2 v = {lo, hi}; const bf16x2_t b = __builtin_convertvector(v, bf16x2_t); return __builtin_bit_cast(unsigned, b); }
; __device__ __forceinline__ void conv2d_phase(const Frame& F, int l, bool with_ctx, bool dry) {
;     ...
;             u32x2 o; o.x = pk2(g0.x * bflo(vv[t].x), g0.y * bfhi(vv[t].x)); o.y = pk2(g1.x * bflo(vv[t].y), g1.y * bfhi(vv[t].y));
;             bf16_t* vp = UV + (size_t)(tok0 + t) * NUP + FFN + ch;
;             if (!dry) *(u32x2*)vp = o; else asm volatile("" :: "v"(o));
.LBB0_2055:
	s_andn2_b64 vcc, exec, s[0:1]
	s_cbranch_vccnz .LBB0_2057
	s_add_i32 s0, s27, 4
	s_mul_hi_i32 s1, s0, 0x2c00
	s_mulk_i32 s0, 0x2c00
	v_readlane_b32 s2, v254, 19
	v_readlane_b32 s3, v254, 20
	s_add_u32 s0, s2, s0
	s_addc_u32 s1, s3, s1
	v_lshl_add_u64 v[80:81], v[42:43], 1, s[0:1]
	v_add_co_u32_e32 v80, vcc, 0x1000, v80
	s_nop 1
	v_addc_co_u32_e32 v81, vcc, 0, v81, vcc
	global_store_dwordx2 v[80:81], v[76:77], off offset:1536 nt

; __device__ __forceinline__ unsigned pk2(float lo, float hi) { const f32x2 v = {lo, hi}; const bf16x2_t b = __builtin_convertvector(v, bf16x2_t); return __builtin_bit_cast(unsigned, b); }
; __device__ __forceinline__ void conv2d_phase(const Frame& F, int l, bool with_ctx, bool dry) {
;     ...
;             u32x2 o; o.x = pk2(g0.x * bflo(vv[t].x), g0.y * bfhi(vv[t].x)); o.y = pk2(g1.x * bflo(vv[t].y), g1.y * bfhi(vv[t].y));
;             bf16_t* vp = UV + (size_t)(tok0 + t) * NUP + FFN + ch;
;             if (!dry) *(u32x2*)vp = o; else asm volatile("" :: "v"(o));
.LBB0_2059:
	s_andn2_b64 vcc, exec, s[0:1]
	s_cbranch_vccnz .LBB0_2061
	s_add_i32 s0, s27, 5
	s_mul_hi_i32 s1, s0, 0x2c00
	s_mulk_i32 s0, 0x2c00
	v_readlane_b32 s2, v254, 19
	v_readlane_b32 s3, v254, 20
	s_add_u32 s0, s2, s0
	s_addc_u32 s1, s3, s1
	v_lshl_add_u64 v[70:71], v[42:43], 1, s[0:1]
	v_add_co_u32_e32 v70, vcc, 0x1000, v70
	s_nop 1
	v_addc_co_u32_e32 v71, vcc, 0, v71, vcc
	global_store_dwordx2 v[70:71], v[66:67], off offset:1536 nt

; __device__ __forceinline__ unsigned pk2(float lo, float hi) { const f32x2 v = {lo, hi}; const bf16x2_t b = __builtin_convertvector(v, bf16x2_t); return __builtin_bit_cast(unsigned, b); }
; __device__ __forceinline__ void conv2d_phase(const Frame& F, int l, bool with_ctx, bool dry) {
;     ...
;             u32x2 o; o.x = pk2(g0.x * bflo(vv[t].x), g0.y * bfhi(vv[t].x)); o.y = pk2(g1.x * bflo(vv[t].y), g1.y * bfhi(vv[t].y));
;             bf16_t* vp = UV + (size_t)(tok0 + t) * NUP + FFN + ch;
;             if (!dry) *(u32x2*)vp = o; else asm volatile("" :: "v"(o));
.LBB0_2063:
	s_andn2_b64 vcc, exec, s[0:1]
	s_cbranch_vccnz .LBB0_2065
	s_add_i32 s0, s27, 6
	s_mul_hi_i32 s1, s0, 0x2c00
	s_mulk_i32 s0, 0x2c00
	v_readlane_b32 s2, v254, 19
	v_readlane_b32 s3, v254, 20
	s_add_u32 s0, s2, s0
	s_addc_u32 s1, s3, s1
	v_lshl_add_u64 v[64:65], v[42:43], 1, s[0:1]
	v_add_co_u32_e32 v64, vcc, 0x1000, v64
	s_nop 1
	v_addc_co_u32_e32 v65, vcc, 0, v65, vcc
	global_store_dwordx2 v[64:65], v[60:61], off offset:1536 nt

; __device__ __forceinline__ unsigned pk2(float lo, float hi) { const f32x2 v = {lo, hi}; const bf16x2_t b = __builtin_convertvector(v, bf16x2_t); return __builtin_bit_cast(unsigned, b); }
; __device__ __forceinline__ void conv2d_phase(const Frame& F, int l, bool with_ctx, bool dry) {
;     ...
;             u32x2 o; o.x = pk2(g0.x * bflo(vv[t].x), g0.y * bfhi(vv[t].x)); o.y = pk2(g1.x * bflo(vv[t].y), g1.y * bfhi(vv[t].y));
;             bf16_t* vp = UV + (size_t)(tok0 + t) * NUP + FFN + ch;
;             if (!dry) *(u32x2*)vp = o; else asm volatile("" :: "v"(o));
.LBB0_2067:
	s_andn2_b64 vcc, exec, s[0:1]
	s_cbranch_vccnz .LBB0_2032
	s_add_i32 s0, s27, 7
	s_mul_hi_i32 s1, s0, 0x2c00
	s_mulk_i32 s0, 0x2c00
	v_readlane_b32 s2, v254, 19
	v_readlane_b32 s3, v254, 20
	s_add_u32 s0, s2, s0
	s_addc_u32 s1, s3, s1
	v_lshl_add_u64 v[4:5], v[42:43], 1, s[0:1]
	v_add_co_u32_e32 v4, vcc, 0x1000, v4
	s_nop 1
	v_addc_co_u32_e32 v5, vcc, 0, v5, vcc
	global_store_dwordx2 v[4:5], v[2:3], off offset:1536 nt
	s_branch .LBB0_2032
